# layer-2 KV-cache bf16 copy loop also two items per trip (four loads in flight)
# speedup vs baseline: 1.0001x; 1.0001x over previous
.LBB0_509:
	s_mov_b32 s4, 0x7ffff
	v_cmp_lt_i32_e32 vcc, s4, v1
	s_waitcnt lgkmcnt(0)
	v_mov_b32_e32 v3, s13
	v_mov_b32_e32 v4, s15
	v_cndmask_b32_e32 v5, v3, v4, vcc
	v_mov_b32_e32 v3, s12
	v_mov_b32_e32 v4, s14
	v_cndmask_b32_e32 v4, v3, v4, vcc
	v_lshlrev_b32_e32 v3, 4, v1
	v_and_b32_e32 v12, 0x700000, v3
	v_and_b32_e32 v3, 0x7fff8, v2
	v_or_b32_e32 v6, v12, v3
	v_lshlrev_b32_e32 v6, 2, v6
	v_mov_b32_e32 v7, v0
	v_lshl_add_u64 v[4:5], v[4:5], 0, v[6:7]
	v_lshl_add_u64 v[8:9], v[4:5], 0, s[56:57]
	v_add_co_u32_e64 v4, s[4:5], s49, v4
	v_mov_b32_e32 v13, v0
	s_nop 0
	v_addc_co_u32_e64 v5, s[4:5], 0, v5, s[4:5]
	global_load_dwordx4 v[4:7], v[4:5], off
	s_nop 0
	global_load_dwordx4 v[8:11], v[8:9], off offset:16
	v_add_u32_e32 v1, s58, v1
	v_add_u32_e32 v2, s59, v2
	s_mov_b32 s4, 0x7ffff
	v_cmp_lt_i32_e64 s[18:19], s4, v1
	v_mov_b32_e32 v73, s13
	v_mov_b32_e32 v74, s15
	v_cndmask_b32_e64 v75, v73, v74, s[18:19]
	v_mov_b32_e32 v73, s12
	v_mov_b32_e32 v74, s14
	v_cndmask_b32_e64 v74, v73, v74, s[18:19]
	v_lshlrev_b32_e32 v73, 4, v1
	v_and_b32_e32 v82, 0x700000, v73
	v_and_b32_e32 v73, 0x7fff8, v2
	v_or_b32_e32 v76, v82, v73
	v_lshlrev_b32_e32 v76, 2, v76
	v_mov_b32_e32 v77, v0
	v_lshl_add_u64 v[74:75], v[74:75], 0, v[76:77]
	v_lshl_add_u64 v[78:79], v[74:75], 0, s[56:57]
	v_add_co_u32_e64 v74, s[4:5], s49, v74
	v_mov_b32_e32 v83, v0
	s_nop 0
	v_addc_co_u32_e64 v75, s[4:5], 0, v75, s[4:5]
	global_load_dwordx4 v[74:77], v[74:75], off
	s_nop 0
	global_load_dwordx4 v[78:81], v[78:79], off offset:16
	v_add_u32_e32 v1, s58, v1
	v_add_u32_e32 v2, s59, v2
	s_waitcnt vmcnt(3)
	v_cvt_pk_bf16_f32 v4, v4, v5
	v_cvt_pk_bf16_f32 v5, v6, v7
	s_waitcnt vmcnt(2)
	v_cvt_pk_bf16_f32 v6, v8, v9
	v_mov_b32_e32 v8, 0x800000
	v_cndmask_b32_e32 v8, 0, v8, vcc
	v_mov_b32_e32 v9, v0
	v_lshl_add_u64 v[8:9], s[16:17], 0, v[8:9]
	v_cvt_pk_bf16_f32 v7, v10, v11
	v_lshl_add_u64 v[8:9], v[8:9], 0, v[12:13]
	v_lshlrev_b32_e32 v10, 1, v3
	v_mov_b32_e32 v11, v0
	v_lshl_add_u64 v[8:9], v[8:9], 0, v[10:11]
	global_store_dwordx4 v[8:9], v[4:7], off
	s_waitcnt vmcnt(2)
	v_cvt_pk_bf16_f32 v74, v74, v75
	v_cvt_pk_bf16_f32 v75, v76, v77
	s_waitcnt vmcnt(1)
	v_cvt_pk_bf16_f32 v76, v78, v79
	v_mov_b32_e32 v78, 0x800000
	v_cndmask_b32_e64 v78, 0, v78, s[18:19]
	v_mov_b32_e32 v79, v0
	v_lshl_add_u64 v[78:79], s[16:17], 0, v[78:79]
	v_cvt_pk_bf16_f32 v77, v80, v81
	v_lshl_add_u64 v[78:79], v[78:79], 0, v[82:83]
	v_lshlrev_b32_e32 v80, 1, v73
	v_mov_b32_e32 v81, v0
	v_lshl_add_u64 v[78:79], v[78:79], 0, v[80:81]
	global_store_dwordx4 v[78:79], v[74:77], off
	s_mov_b32 s4, 0xfffff
	v_cmp_lt_i32_e32 vcc, s4, v1
	s_or_b64 s[20:21], vcc, s[20:21]
	s_andn2_b64 exec, exec, s[20:21]
	s_cbranch_execnz .LBB0_509
